# XCD-local barriers: fire-and-forget arrival + polling the arrival word (no ticket round trip, no generation hop); rest as v058
# baseline (speedup 1.0000x reference)
.LBB0_436:
	v_mbcnt_lo_u32_b32 v0, -1, 0
	v_mbcnt_hi_u32_b32 v0, -1, v0
	s_waitcnt vmcnt(0)
	v_readlane_b32 s4, v254, 6
	v_sub_u32_e32 v0, 0, v0
	s_waitcnt lgkmcnt(0)
	v_cmp_eq_u32_e32 vcc, s4, v0
	s_barrier
	s_and_saveexec_b64 s[4:5], vcc
	s_cbranch_execz .LBB0_488
	v_readlane_b32 s6, v255, 0
	s_nop 3
	s_cmp_eq_u32 s6, 0
	s_cbranch_scc1 .Lxl_b4_global
	v_mov_b32_e32 v0, 0x20400
	ds_read_b32 v2, v0
	v_readlane_b32 s6, v254, 0
	s_nop 3
	s_lshl_b32 s6, s6, 8
	s_add_u32 s6, s6, 0x40000
	s_add_u32 s6, s66, s6
	s_addc_u32 s7, s67, 0
	v_mov_b32_e32 v3, 0x1400
	v_mov_b32_e32 v4, 1
	s_waitcnt lgkmcnt(0)
	v_readfirstlane_b32 s8, v2
	global_atomic_add v3, v4, s[6:7]
	s_mul_i32 s10, s8, 4
	s_mov_b32 s11, 0
.Lxl_b4_spin:
	global_load_dword v5, v3, s[6:7] sc1
	s_waitcnt vmcnt(0)
	v_readfirstlane_b32 s9, v5
	s_cmp_ge_u32 s9, s10
	s_cbranch_scc1 .Lxl_b4_acq
	s_sleep 1
	s_add_i32 s11, s11, 1
	s_cmp_lt_u32 s11, 1048576
	s_cbranch_scc1 .Lxl_b4_spin

.LBB0_514:
	v_mbcnt_lo_u32_b32 v0, -1, 0
	v_mbcnt_hi_u32_b32 v0, -1, v0
	s_waitcnt vmcnt(0)
	v_readlane_b32 s4, v254, 6
	v_sub_u32_e32 v0, 0, v0
	s_waitcnt vmcnt(0)
	v_cmp_eq_u32_e32 vcc, s4, v0
	s_barrier
	s_and_saveexec_b64 s[4:5], vcc
	s_cbranch_execz .LBB0_566
	v_readlane_b32 s6, v255, 0
	s_nop 3
	s_cmp_eq_u32 s6, 0
	s_cbranch_scc1 .Lxl_b5_global
	v_mov_b32_e32 v0, 0x20400
	ds_read_b32 v2, v0
	v_readlane_b32 s6, v254, 0
	s_nop 3
	s_lshl_b32 s6, s6, 8
	s_add_u32 s6, s6, 0x40000
	s_add_u32 s6, s66, s6
	s_addc_u32 s7, s67, 0
	v_mov_b32_e32 v3, 0x1400
	v_mov_b32_e32 v4, 1
	s_waitcnt lgkmcnt(0)
	v_readfirstlane_b32 s8, v2
	global_atomic_add v3, v4, s[6:7]
	s_mul_i32 s10, s8, 5
	s_mov_b32 s11, 0
